# stack: P6 split128 + attention prefetch/vmcnt fix + coalesced sk_tile P2/P12 + barrier local release by plain store
# speedup vs baseline: 1.0072x; 1.0072x over previous
; __device__ __forceinline__ unsigned xb_ld(unsigned* p)              { return __hip_atomic_load(p, __ATOMIC_RELAXED, __HIP_MEMORY_SCOPE_AGENT); }
; __device__ __forceinline__ unsigned xb_add(unsigned* p, unsigned v) { return __hip_atomic_fetch_add(p, v, __ATOMIC_RELAXED, __HIP_MEMORY_SCOPE_AGENT); }
; #define XB_SPIN(cond, bar) do { unsigned _sp = 0; while (cond) { __builtin_amdgcn_s_sleep(1); \
;     if ((++_sp & 255u) == 0u) { if (xb_ld(&(bar)[XB_TMO])) break; if (_sp > XB_SPIN_CAP) { atomicAdd(&(bar)[XB_TMO], 1u); break; } } } } while (0)
; __device__ __forceinline__ void xcd_barrier(const XcdBarrier& b) {
;     ...
;         const unsigned old = xb_add(&bar[XB_XSUB(b.x)], 1u);
;         const unsigned gen = old / nloc;
;         if (old + 1u == (gen + 1u) * nloc) {
;             __builtin_amdgcn_fence(__ATOMIC_RELEASE, "agent");
;             asm volatile("s_waitcnt vmcnt(0)" ::: "memory");
;             const unsigned og = xb_add(&bar[XB_TOP], 1u);
;             const unsigned tg = og / nx;
;             if (og + 1u == (tg + 1u) * nx) xb_add(&bar[XB_TOPGEN], 1u);
;             else XB_SPIN(xb_ld(&bar[XB_TOPGEN]) == tg, bar);
;             __builtin_amdgcn_fence(__ATOMIC_ACQUIRE, "agent");
;             xb_add(&bar[XB_XGEN(b.x)], 1u);
;             asm volatile("s_waitcnt vmcnt(0)" ::: "memory");
;         } else {
;             XB_SPIN(xb_ld(&bar[XB_XGEN(b.x)]) == gen, bar);
.LBB0_48:
	s_or_b64 exec, exec, s[10:11]
	v_cvt_f32_u32_e32 v6, v4
	s_waitcnt vmcnt(0)
	v_readfirstlane_b32 s6, v5
	v_sub_u32_e32 v5, 0, v4
	v_rcp_iflag_f32_e32 v6, v6
	v_add_u32_e32 v7, s6, v3
	v_mul_f32_e32 v6, 0x4f7ffffe, v6
	v_cvt_u32_f32_e32 v6, v6
	v_mul_lo_u32 v3, v5, v6
	v_mul_hi_u32 v3, v6, v3
	v_add_u32_e32 v3, v6, v3
	v_mul_hi_u32 v3, v7, v3
	v_mul_lo_u32 v5, v3, v4
	v_sub_u32_e32 v5, v7, v5
	v_add_u32_e32 v6, 1, v3
	v_cmp_ge_u32_e32 vcc, v5, v4
	s_nop 1
	v_cndmask_b32_e32 v3, v3, v6, vcc
	v_sub_u32_e32 v6, v5, v4
	v_cndmask_b32_e32 v5, v5, v6, vcc
	v_add_u32_e32 v6, 1, v3
	v_cmp_ge_u32_e32 vcc, v5, v4
	v_add_u32_e32 v5, 1, v7
	s_nop 0
	v_cndmask_b32_e32 v3, v3, v6, vcc
	v_mul_lo_u32 v6, v4, v3
	v_add_u32_e32 v253, 1, v3
	v_add_u32_e32 v4, v6, v4
	v_cmp_ne_u32_e32 vcc, v5, v4
	s_and_saveexec_b64 s[6:7], vcc
	s_xor_b64 s[6:7], exec, s[6:7]
	s_cbranch_execz .LBB0_62
	s_waitcnt lgkmcnt(0)
	v_mov_b32_e32 v2, 0x2000
	global_load_dword v2, v2, s[2:3] offset:1024 sc1
	s_add_u32 s14, s2, 0x2400
	s_addc_u32 s15, s3, 0
	s_waitcnt vmcnt(0)
	v_cmp_eq_u32_e32 vcc, v2, v3
	s_and_saveexec_b64 s[10:11], vcc
	s_cbranch_execz .LBB0_61
	s_add_u32 s12, s90, 0x4200
	s_addc_u32 s13, s91, 0
	s_mov_b32 s26, 1
	s_mov_b64 s[16:17], 0
	v_mov_b32_e32 v2, 0
	s_branch .LBB0_52

; __device__ __forceinline__ unsigned xb_ld(unsigned* p)              { return __hip_atomic_load(p, __ATOMIC_RELAXED, __HIP_MEMORY_SCOPE_AGENT); }
; __device__ __forceinline__ unsigned xb_add(unsigned* p, unsigned v) { return __hip_atomic_fetch_add(p, v, __ATOMIC_RELAXED, __HIP_MEMORY_SCOPE_AGENT); }
; #define XB_SPIN(cond, bar) do { unsigned _sp = 0; while (cond) { __builtin_amdgcn_s_sleep(1); \
;     if ((++_sp & 255u) == 0u) { if (xb_ld(&(bar)[XB_TMO])) break; if (_sp > XB_SPIN_CAP) { atomicAdd(&(bar)[XB_TMO], 1u); break; } } } } while (0)
; __device__ __forceinline__ void xcd_barrier(const XcdBarrier& b) {
;     ...
;             if (og + 1u == (tg + 1u) * nx) xb_add(&bar[XB_TOPGEN], 1u);
;             else XB_SPIN(xb_ld(&bar[XB_TOPGEN]) == tg, bar);
;             __builtin_amdgcn_fence(__ATOMIC_ACQUIRE, "agent");
;             xb_add(&bar[XB_XGEN(b.x)], 1u);
;             asm volatile("s_waitcnt vmcnt(0)" ::: "memory");
.LBB0_79:
	s_or_b64 exec, exec, s[6:7]
	s_mov_b64 s[6:7], exec
	v_mbcnt_lo_u32_b32 v2, s6, 0
	v_mbcnt_hi_u32_b32 v2, s7, v2
	v_cmp_eq_u32_e32 vcc, 0, v2
	s_waitcnt vmcnt(0)
	buffer_inv sc1
	s_and_saveexec_b64 s[10:11], vcc
	s_cbranch_execz .LBB0_81
	s_bcnt1_i32_b64 s6, s[6:7]
	v_mov_b32_e32 v2, 0x2000
	v_mov_b32_e32 v3, s6
	global_store_dword v2, v253, s[2:3] offset:1024

; __device__ __forceinline__ unsigned xb_ld(unsigned* p)              { return __hip_atomic_load(p, __ATOMIC_RELAXED, __HIP_MEMORY_SCOPE_AGENT); }
; __device__ __forceinline__ unsigned xb_add(unsigned* p, unsigned v) { return __hip_atomic_fetch_add(p, v, __ATOMIC_RELAXED, __HIP_MEMORY_SCOPE_AGENT); }
; #define XB_SPIN(cond, bar) do { unsigned _sp = 0; while (cond) { __builtin_amdgcn_s_sleep(1); \
;     if ((++_sp & 255u) == 0u) { if (xb_ld(&(bar)[XB_TMO])) break; if (_sp > XB_SPIN_CAP) { atomicAdd(&(bar)[XB_TMO], 1u); break; } } } } while (0)
; __device__ __forceinline__ void xcd_barrier(const XcdBarrier& b) {
;     ...
;         const unsigned old = xb_add(&bar[XB_XSUB(b.x)], 1u);
;         const unsigned gen = old / nloc;
;         if (old + 1u == (gen + 1u) * nloc) {
;             __builtin_amdgcn_fence(__ATOMIC_RELEASE, "agent");
;             asm volatile("s_waitcnt vmcnt(0)" ::: "memory");
;             const unsigned og = xb_add(&bar[XB_TOP], 1u);
;             const unsigned tg = og / nx;
;             if (og + 1u == (tg + 1u) * nx) xb_add(&bar[XB_TOPGEN], 1u);
;             else XB_SPIN(xb_ld(&bar[XB_TOPGEN]) == tg, bar);
;             __builtin_amdgcn_fence(__ATOMIC_ACQUIRE, "agent");
;             xb_add(&bar[XB_XGEN(b.x)], 1u);
;             asm volatile("s_waitcnt vmcnt(0)" ::: "memory");
;         } else {
;             XB_SPIN(xb_ld(&bar[XB_XGEN(b.x)]) == gen, bar);
.LBB0_367:
	s_or_b64 exec, exec, s[6:7]
	v_cvt_f32_u32_e32 v6, v4
	s_waitcnt vmcnt(0)
	v_readfirstlane_b32 s4, v5
	v_sub_u32_e32 v5, 0, v4
	v_rcp_iflag_f32_e32 v6, v6
	v_add_u32_e32 v7, s4, v3
	v_mul_f32_e32 v6, 0x4f7ffffe, v6
	v_cvt_u32_f32_e32 v6, v6
	v_mul_lo_u32 v3, v5, v6
	v_mul_hi_u32 v3, v6, v3
	v_add_u32_e32 v3, v6, v3
	v_mul_hi_u32 v3, v7, v3
	v_mul_lo_u32 v5, v3, v4
	v_sub_u32_e32 v5, v7, v5
	v_add_u32_e32 v6, 1, v3
	v_cmp_ge_u32_e32 vcc, v5, v4
	s_nop 1
	v_cndmask_b32_e32 v3, v3, v6, vcc
	v_sub_u32_e32 v6, v5, v4
	v_cndmask_b32_e32 v5, v5, v6, vcc
	v_add_u32_e32 v6, 1, v3
	v_cmp_ge_u32_e32 vcc, v5, v4
	v_add_u32_e32 v5, 1, v7
	s_nop 0
	v_cndmask_b32_e32 v3, v3, v6, vcc
	v_mul_lo_u32 v6, v4, v3
	v_add_u32_e32 v253, 1, v3
	v_add_u32_e32 v4, v6, v4
	v_cmp_ne_u32_e32 vcc, v5, v4
	s_and_saveexec_b64 s[4:5], vcc
	s_xor_b64 s[4:5], exec, s[4:5]
	s_cbranch_execz .LBB0_381
	s_waitcnt lgkmcnt(0)
	v_mov_b32_e32 v2, 0x2000
	global_load_dword v2, v2, s[2:3] offset:1024 sc1
	s_add_u32 s18, s2, 0x2400
	s_addc_u32 s19, s3, 0
	s_waitcnt vmcnt(0)
	v_cmp_eq_u32_e32 vcc, v2, v3
	s_and_saveexec_b64 s[6:7], vcc
	s_cbranch_execz .LBB0_380
	s_add_u32 s14, s90, 0x4200
	s_addc_u32 s15, s91, 0
	s_mov_b32 s30, 1
	s_mov_b64 s[20:21], 0
	v_mov_b32_e32 v2, 0
	s_branch .LBB0_371

; __device__ __forceinline__ unsigned xb_ld(unsigned* p)              { return __hip_atomic_load(p, __ATOMIC_RELAXED, __HIP_MEMORY_SCOPE_AGENT); }
; __device__ __forceinline__ unsigned xb_add(unsigned* p, unsigned v) { return __hip_atomic_fetch_add(p, v, __ATOMIC_RELAXED, __HIP_MEMORY_SCOPE_AGENT); }
; #define XB_SPIN(cond, bar) do { unsigned _sp = 0; while (cond) { __builtin_amdgcn_s_sleep(1); \
;     if ((++_sp & 255u) == 0u) { if (xb_ld(&(bar)[XB_TMO])) break; if (_sp > XB_SPIN_CAP) { atomicAdd(&(bar)[XB_TMO], 1u); break; } } } } while (0)
; __device__ __forceinline__ void xcd_barrier(const XcdBarrier& b) {
;     ...
;             if (og + 1u == (tg + 1u) * nx) xb_add(&bar[XB_TOPGEN], 1u);
;             else XB_SPIN(xb_ld(&bar[XB_TOPGEN]) == tg, bar);
;             __builtin_amdgcn_fence(__ATOMIC_ACQUIRE, "agent");
;             xb_add(&bar[XB_XGEN(b.x)], 1u);
;             asm volatile("s_waitcnt vmcnt(0)" ::: "memory");
.LBB0_398:
	s_or_b64 exec, exec, s[4:5]
	s_mov_b64 s[4:5], exec
	v_mbcnt_lo_u32_b32 v2, s4, 0
	v_mbcnt_hi_u32_b32 v2, s5, v2
	v_cmp_eq_u32_e32 vcc, 0, v2
	s_waitcnt vmcnt(0)
	buffer_inv sc1
	s_and_saveexec_b64 s[6:7], vcc
	s_cbranch_execz .LBB0_400
	s_bcnt1_i32_b64 s4, s[4:5]
	v_mov_b32_e32 v2, 0x2000
	v_mov_b32_e32 v3, s4
	global_store_dword v2, v253, s[2:3] offset:1024

; __device__ __forceinline__ unsigned xb_ld(unsigned* p)              { return __hip_atomic_load(p, __ATOMIC_RELAXED, __HIP_MEMORY_SCOPE_AGENT); }
; __device__ __forceinline__ unsigned xb_add(unsigned* p, unsigned v) { return __hip_atomic_fetch_add(p, v, __ATOMIC_RELAXED, __HIP_MEMORY_SCOPE_AGENT); }
; #define XB_SPIN(cond, bar) do { unsigned _sp = 0; while (cond) { __builtin_amdgcn_s_sleep(1); \
;     if ((++_sp & 255u) == 0u) { if (xb_ld(&(bar)[XB_TMO])) break; if (_sp > XB_SPIN_CAP) { atomicAdd(&(bar)[XB_TMO], 1u); break; } } } } while (0)
; __device__ __forceinline__ void xcd_barrier(const XcdBarrier& b) {
;     ...
;         const unsigned old = xb_add(&bar[XB_XSUB(b.x)], 1u);
;         const unsigned gen = old / nloc;
;         if (old + 1u == (gen + 1u) * nloc) {
;             __builtin_amdgcn_fence(__ATOMIC_RELEASE, "agent");
;             asm volatile("s_waitcnt vmcnt(0)" ::: "memory");
;             const unsigned og = xb_add(&bar[XB_TOP], 1u);
;             const unsigned tg = og / nx;
;             if (og + 1u == (tg + 1u) * nx) xb_add(&bar[XB_TOPGEN], 1u);
;             else XB_SPIN(xb_ld(&bar[XB_TOPGEN]) == tg, bar);
;             __builtin_amdgcn_fence(__ATOMIC_ACQUIRE, "agent");
;             xb_add(&bar[XB_XGEN(b.x)], 1u);
;             asm volatile("s_waitcnt vmcnt(0)" ::: "memory");
;         } else {
;             XB_SPIN(xb_ld(&bar[XB_XGEN(b.x)]) == gen, bar);
.LBB0_448:
	s_or_b64 exec, exec, s[6:7]
	v_cvt_f32_u32_e32 v6, v4
	s_waitcnt vmcnt(0)
	v_readfirstlane_b32 s4, v5
	v_sub_u32_e32 v5, 0, v4
	v_rcp_iflag_f32_e32 v6, v6
	v_add_u32_e32 v7, s4, v3
	v_mul_f32_e32 v6, 0x4f7ffffe, v6
	v_cvt_u32_f32_e32 v6, v6
	v_mul_lo_u32 v3, v5, v6
	v_mul_hi_u32 v3, v6, v3
	v_add_u32_e32 v3, v6, v3
	v_mul_hi_u32 v3, v7, v3
	v_mul_lo_u32 v5, v3, v4
	v_sub_u32_e32 v5, v7, v5
	v_add_u32_e32 v6, 1, v3
	v_cmp_ge_u32_e32 vcc, v5, v4
	s_nop 1
	v_cndmask_b32_e32 v3, v3, v6, vcc
	v_sub_u32_e32 v6, v5, v4
	v_cndmask_b32_e32 v5, v5, v6, vcc
	v_add_u32_e32 v6, 1, v3
	v_cmp_ge_u32_e32 vcc, v5, v4
	v_add_u32_e32 v5, 1, v7
	s_nop 0
	v_cndmask_b32_e32 v3, v3, v6, vcc
	v_mul_lo_u32 v6, v4, v3
	v_add_u32_e32 v253, 1, v3
	v_add_u32_e32 v4, v6, v4
	v_cmp_ne_u32_e32 vcc, v5, v4
	s_and_saveexec_b64 s[4:5], vcc
	s_xor_b64 s[4:5], exec, s[4:5]
	s_cbranch_execz .LBB0_462
	s_waitcnt lgkmcnt(0)
	v_mov_b32_e32 v2, 0x2000
	global_load_dword v2, v2, s[2:3] offset:1024 sc1
	s_add_u32 s18, s2, 0x2400
	s_addc_u32 s19, s3, 0
	s_waitcnt vmcnt(0)
	v_cmp_eq_u32_e32 vcc, v2, v3
	s_and_saveexec_b64 s[6:7], vcc
	s_cbranch_execz .LBB0_461
	s_add_u32 s16, s90, 0x4200
	s_addc_u32 s17, s91, 0
	s_mov_b32 s30, 1
	s_mov_b64 s[20:21], 0
	v_mov_b32_e32 v2, 0
	s_branch .LBB0_452

; __device__ __forceinline__ unsigned xb_ld(unsigned* p)              { return __hip_atomic_load(p, __ATOMIC_RELAXED, __HIP_MEMORY_SCOPE_AGENT); }
; __device__ __forceinline__ unsigned xb_add(unsigned* p, unsigned v) { return __hip_atomic_fetch_add(p, v, __ATOMIC_RELAXED, __HIP_MEMORY_SCOPE_AGENT); }
; #define XB_SPIN(cond, bar) do { unsigned _sp = 0; while (cond) { __builtin_amdgcn_s_sleep(1); \
;     if ((++_sp & 255u) == 0u) { if (xb_ld(&(bar)[XB_TMO])) break; if (_sp > XB_SPIN_CAP) { atomicAdd(&(bar)[XB_TMO], 1u); break; } } } } while (0)
; __device__ __forceinline__ void xcd_barrier(const XcdBarrier& b) {
;     ...
;         const unsigned old = xb_add(&bar[XB_XSUB(b.x)], 1u);
;         const unsigned gen = old / nloc;
;         if (old + 1u == (gen + 1u) * nloc) {
;             __builtin_amdgcn_fence(__ATOMIC_RELEASE, "agent");
;             asm volatile("s_waitcnt vmcnt(0)" ::: "memory");
;             const unsigned og = xb_add(&bar[XB_TOP], 1u);
;             const unsigned tg = og / nx;
;             if (og + 1u == (tg + 1u) * nx) xb_add(&bar[XB_TOPGEN], 1u);
;             else XB_SPIN(xb_ld(&bar[XB_TOPGEN]) == tg, bar);
;             __builtin_amdgcn_fence(__ATOMIC_ACQUIRE, "agent");
;             xb_add(&bar[XB_XGEN(b.x)], 1u);
;             asm volatile("s_waitcnt vmcnt(0)" ::: "memory");
;         } else {
;             XB_SPIN(xb_ld(&bar[XB_XGEN(b.x)]) == gen, bar);
.LBB0_510:
	s_or_b64 exec, exec, s[6:7]
	v_cvt_f32_u32_e32 v6, v4
	s_waitcnt vmcnt(0)
	v_readfirstlane_b32 s4, v5
	v_sub_u32_e32 v5, 0, v4
	v_rcp_iflag_f32_e32 v6, v6
	v_add_u32_e32 v7, s4, v3
	v_mul_f32_e32 v6, 0x4f7ffffe, v6
	v_cvt_u32_f32_e32 v6, v6
	v_mul_lo_u32 v3, v5, v6
	v_mul_hi_u32 v3, v6, v3
	v_add_u32_e32 v3, v6, v3
	v_mul_hi_u32 v3, v7, v3
	v_mul_lo_u32 v5, v3, v4
	v_sub_u32_e32 v5, v7, v5
	v_add_u32_e32 v6, 1, v3
	v_cmp_ge_u32_e32 vcc, v5, v4
	s_nop 1
	v_cndmask_b32_e32 v3, v3, v6, vcc
	v_sub_u32_e32 v6, v5, v4
	v_cndmask_b32_e32 v5, v5, v6, vcc
	v_add_u32_e32 v6, 1, v3
	v_cmp_ge_u32_e32 vcc, v5, v4
	v_add_u32_e32 v5, 1, v7
	s_nop 0
	v_cndmask_b32_e32 v3, v3, v6, vcc
	v_mul_lo_u32 v6, v4, v3
	v_add_u32_e32 v253, 1, v3
	v_add_u32_e32 v4, v6, v4
	v_cmp_ne_u32_e32 vcc, v5, v4
	s_and_saveexec_b64 s[4:5], vcc
	s_xor_b64 s[4:5], exec, s[4:5]
	s_cbranch_execz .LBB0_524
	s_waitcnt lgkmcnt(0)
	v_mov_b32_e32 v2, 0x2000
	global_load_dword v2, v2, s[2:3] offset:1024 sc1
	s_add_u32 s16, s2, 0x2400
	s_addc_u32 s17, s3, 0
	s_waitcnt vmcnt(0)
	v_cmp_eq_u32_e32 vcc, v2, v3
	s_and_saveexec_b64 s[6:7], vcc
	s_cbranch_execz .LBB0_523
	s_add_u32 s8, s90, 0x4200
	s_addc_u32 s9, s91, 0
	s_mov_b32 s28, 1
	s_mov_b64 s[18:19], 0
	v_mov_b32_e32 v2, 0
	s_branch .LBB0_514

; __device__ __forceinline__ unsigned xb_ld(unsigned* p)              { return __hip_atomic_load(p, __ATOMIC_RELAXED, __HIP_MEMORY_SCOPE_AGENT); }
; __device__ __forceinline__ unsigned xb_add(unsigned* p, unsigned v) { return __hip_atomic_fetch_add(p, v, __ATOMIC_RELAXED, __HIP_MEMORY_SCOPE_AGENT); }
; #define XB_SPIN(cond, bar) do { unsigned _sp = 0; while (cond) { __builtin_amdgcn_s_sleep(1); \
;     if ((++_sp & 255u) == 0u) { if (xb_ld(&(bar)[XB_TMO])) break; if (_sp > XB_SPIN_CAP) { atomicAdd(&(bar)[XB_TMO], 1u); break; } } } } while (0)
; __device__ __forceinline__ void xcd_barrier(const XcdBarrier& b) {
;     ...
;         const unsigned old = xb_add(&bar[XB_XSUB(b.x)], 1u);
;         const unsigned gen = old / nloc;
;         if (old + 1u == (gen + 1u) * nloc) {
;             __builtin_amdgcn_fence(__ATOMIC_RELEASE, "agent");
;             asm volatile("s_waitcnt vmcnt(0)" ::: "memory");
;             const unsigned og = xb_add(&bar[XB_TOP], 1u);
;             const unsigned tg = og / nx;
;             if (og + 1u == (tg + 1u) * nx) xb_add(&bar[XB_TOPGEN], 1u);
;             else XB_SPIN(xb_ld(&bar[XB_TOPGEN]) == tg, bar);
;             __builtin_amdgcn_fence(__ATOMIC_ACQUIRE, "agent");
;             xb_add(&bar[XB_XGEN(b.x)], 1u);
;             asm volatile("s_waitcnt vmcnt(0)" ::: "memory");
;         } else {
;             XB_SPIN(xb_ld(&bar[XB_XGEN(b.x)]) == gen, bar);
.LBB0_915:
	s_or_b64 exec, exec, s[6:7]
	v_cvt_f32_u32_e32 v6, v4
	s_waitcnt vmcnt(0)
	v_readfirstlane_b32 s4, v5
	v_sub_u32_e32 v5, 0, v4
	v_rcp_iflag_f32_e32 v6, v6
	v_add_u32_e32 v7, s4, v3
	v_mul_f32_e32 v6, 0x4f7ffffe, v6
	v_cvt_u32_f32_e32 v6, v6
	v_mul_lo_u32 v3, v5, v6
	v_mul_hi_u32 v3, v6, v3
	v_add_u32_e32 v3, v6, v3
	v_mul_hi_u32 v3, v7, v3
	v_mul_lo_u32 v5, v3, v4
	v_sub_u32_e32 v5, v7, v5
	v_add_u32_e32 v6, 1, v3
	v_cmp_ge_u32_e32 vcc, v5, v4
	s_nop 1
	v_cndmask_b32_e32 v3, v3, v6, vcc
	v_sub_u32_e32 v6, v5, v4
	v_cndmask_b32_e32 v5, v5, v6, vcc
	v_add_u32_e32 v6, 1, v3
	v_cmp_ge_u32_e32 vcc, v5, v4
	v_add_u32_e32 v5, 1, v7
	s_nop 0
	v_cndmask_b32_e32 v3, v3, v6, vcc
	v_mul_lo_u32 v6, v4, v3
	v_add_u32_e32 v253, 1, v3
	v_add_u32_e32 v4, v6, v4
	v_cmp_ne_u32_e32 vcc, v5, v4
	s_and_saveexec_b64 s[4:5], vcc
	s_xor_b64 s[4:5], exec, s[4:5]
	s_cbranch_execz .LBB0_929
	s_waitcnt lgkmcnt(0)
	v_mov_b32_e32 v2, 0x2000
	global_load_dword v2, v2, s[2:3] offset:1024 sc1
	s_add_u32 s10, s2, 0x2400
	s_addc_u32 s11, s3, 0
	s_waitcnt vmcnt(0)
	v_cmp_eq_u32_e32 vcc, v2, v3
	s_and_saveexec_b64 s[6:7], vcc
	s_cbranch_execz .LBB0_928
	s_add_u32 s8, s90, 0x4200
	s_addc_u32 s9, s91, 0
	s_mov_b32 s22, 1
	s_mov_b64 s[12:13], 0
	v_mov_b32_e32 v2, 0
	s_branch .LBB0_919

; __device__ __forceinline__ unsigned xb_ld(unsigned* p)              { return __hip_atomic_load(p, __ATOMIC_RELAXED, __HIP_MEMORY_SCOPE_AGENT); }
; __device__ __forceinline__ unsigned xb_add(unsigned* p, unsigned v) { return __hip_atomic_fetch_add(p, v, __ATOMIC_RELAXED, __HIP_MEMORY_SCOPE_AGENT); }
; #define XB_SPIN(cond, bar) do { unsigned _sp = 0; while (cond) { __builtin_amdgcn_s_sleep(1); \
;     if ((++_sp & 255u) == 0u) { if (xb_ld(&(bar)[XB_TMO])) break; if (_sp > XB_SPIN_CAP) { atomicAdd(&(bar)[XB_TMO], 1u); break; } } } } while (0)
; __device__ __forceinline__ void xcd_barrier(const XcdBarrier& b) {
;     ...
;         const unsigned old = xb_add(&bar[XB_XSUB(b.x)], 1u);
;         const unsigned gen = old / nloc;
;         if (old + 1u == (gen + 1u) * nloc) {
;             __builtin_amdgcn_fence(__ATOMIC_RELEASE, "agent");
;             asm volatile("s_waitcnt vmcnt(0)" ::: "memory");
;             const unsigned og = xb_add(&bar[XB_TOP], 1u);
;             const unsigned tg = og / nx;
;             if (og + 1u == (tg + 1u) * nx) xb_add(&bar[XB_TOPGEN], 1u);
;             else XB_SPIN(xb_ld(&bar[XB_TOPGEN]) == tg, bar);
;             __builtin_amdgcn_fence(__ATOMIC_ACQUIRE, "agent");
;             xb_add(&bar[XB_XGEN(b.x)], 1u);
;             asm volatile("s_waitcnt vmcnt(0)" ::: "memory");
;         } else {
;             XB_SPIN(xb_ld(&bar[XB_XGEN(b.x)]) == gen, bar);
.LBB0_1300:
	s_or_b64 exec, exec, s[8:9]
	v_cvt_f32_u32_e32 v6, v4
	s_waitcnt vmcnt(0)
	v_readfirstlane_b32 s2, v5
	v_sub_u32_e32 v5, 0, v4
	v_rcp_iflag_f32_e32 v6, v6
	v_add_u32_e32 v7, s2, v3
	v_mul_f32_e32 v6, 0x4f7ffffe, v6
	v_cvt_u32_f32_e32 v6, v6
	v_mul_lo_u32 v3, v5, v6
	v_mul_hi_u32 v3, v6, v3
	v_add_u32_e32 v3, v6, v3
	v_mul_hi_u32 v3, v7, v3
	v_mul_lo_u32 v5, v3, v4
	v_sub_u32_e32 v5, v7, v5
	v_add_u32_e32 v6, 1, v3
	v_cmp_ge_u32_e32 vcc, v5, v4
	s_nop 1
	v_cndmask_b32_e32 v3, v3, v6, vcc
	v_sub_u32_e32 v6, v5, v4
	v_cndmask_b32_e32 v5, v5, v6, vcc
	v_add_u32_e32 v6, 1, v3
	v_cmp_ge_u32_e32 vcc, v5, v4
	v_add_u32_e32 v5, 1, v7
	s_nop 0
	v_cndmask_b32_e32 v3, v3, v6, vcc
	v_mul_lo_u32 v6, v4, v3
	v_add_u32_e32 v253, 1, v3
	v_add_u32_e32 v4, v6, v4
	v_cmp_ne_u32_e32 vcc, v5, v4
	s_and_saveexec_b64 s[2:3], vcc
	s_xor_b64 s[6:7], exec, s[2:3]
	s_cbranch_execz .LBB0_1314
	s_waitcnt lgkmcnt(0)
	v_mov_b32_e32 v2, 0x2000
	global_load_dword v2, v2, s[4:5] offset:1024 sc1
	s_add_u32 s12, s4, 0x2400
	s_addc_u32 s13, s5, 0
	s_waitcnt vmcnt(0)
	v_cmp_eq_u32_e32 vcc, v2, v3
	s_and_saveexec_b64 s[8:9], vcc
	s_cbranch_execz .LBB0_1313
	s_add_u32 s10, s90, 0x4200
	s_addc_u32 s11, s91, 0
	s_mov_b32 s2, 1
	s_mov_b64 s[18:19], 0
	v_mov_b32_e32 v2, 0
	s_branch .LBB0_1304

; __device__ __forceinline__ unsigned xb_ld(unsigned* p)              { return __hip_atomic_load(p, __ATOMIC_RELAXED, __HIP_MEMORY_SCOPE_AGENT); }
; __device__ __forceinline__ unsigned xb_add(unsigned* p, unsigned v) { return __hip_atomic_fetch_add(p, v, __ATOMIC_RELAXED, __HIP_MEMORY_SCOPE_AGENT); }
; #define XB_SPIN(cond, bar) do { unsigned _sp = 0; while (cond) { __builtin_amdgcn_s_sleep(1); \
;     if ((++_sp & 255u) == 0u) { if (xb_ld(&(bar)[XB_TMO])) break; if (_sp > XB_SPIN_CAP) { atomicAdd(&(bar)[XB_TMO], 1u); break; } } } } while (0)
; __device__ __forceinline__ void xcd_barrier(const XcdBarrier& b) {
;     ...
;             if (og + 1u == (tg + 1u) * nx) xb_add(&bar[XB_TOPGEN], 1u);
;             else XB_SPIN(xb_ld(&bar[XB_TOPGEN]) == tg, bar);
;             __builtin_amdgcn_fence(__ATOMIC_ACQUIRE, "agent");
;             xb_add(&bar[XB_XGEN(b.x)], 1u);
;             asm volatile("s_waitcnt vmcnt(0)" ::: "memory");
.LBB0_1331:
	s_or_b64 exec, exec, s[6:7]
	s_mov_b64 s[6:7], exec
	v_mbcnt_lo_u32_b32 v2, s6, 0
	v_mbcnt_hi_u32_b32 v2, s7, v2
	v_cmp_eq_u32_e32 vcc, 0, v2
	s_waitcnt vmcnt(0)
	buffer_inv sc1
	s_and_saveexec_b64 s[8:9], vcc
	s_cbranch_execz .LBB0_1333
	s_bcnt1_i32_b64 s2, s[6:7]
	v_mov_b32_e32 v2, 0x2000
	v_mov_b32_e32 v3, s2
	global_store_dword v2, v253, s[4:5] offset:1024

; __device__ __forceinline__ unsigned xb_ld(unsigned* p)              { return __hip_atomic_load(p, __ATOMIC_RELAXED, __HIP_MEMORY_SCOPE_AGENT); }
; __device__ __forceinline__ unsigned xb_add(unsigned* p, unsigned v) { return __hip_atomic_fetch_add(p, v, __ATOMIC_RELAXED, __HIP_MEMORY_SCOPE_AGENT); }
; #define XB_SPIN(cond, bar) do { unsigned _sp = 0; while (cond) { __builtin_amdgcn_s_sleep(1); \
;     if ((++_sp & 255u) == 0u) { if (xb_ld(&(bar)[XB_TMO])) break; if (_sp > XB_SPIN_CAP) { atomicAdd(&(bar)[XB_TMO], 1u); break; } } } } while (0)
; __device__ __forceinline__ void xcd_barrier(const XcdBarrier& b) {
;     ...
;         const unsigned old = xb_add(&bar[XB_XSUB(b.x)], 1u);
;         const unsigned gen = old / nloc;
;         if (old + 1u == (gen + 1u) * nloc) {
;             __builtin_amdgcn_fence(__ATOMIC_RELEASE, "agent");
;             asm volatile("s_waitcnt vmcnt(0)" ::: "memory");
;             const unsigned og = xb_add(&bar[XB_TOP], 1u);
;             const unsigned tg = og / nx;
;             if (og + 1u == (tg + 1u) * nx) xb_add(&bar[XB_TOPGEN], 1u);
;             else XB_SPIN(xb_ld(&bar[XB_TOPGEN]) == tg, bar);
;             __builtin_amdgcn_fence(__ATOMIC_ACQUIRE, "agent");
;             xb_add(&bar[XB_XGEN(b.x)], 1u);
;             asm volatile("s_waitcnt vmcnt(0)" ::: "memory");
;         } else {
;             XB_SPIN(xb_ld(&bar[XB_XGEN(b.x)]) == gen, bar);
.LBB0_1372:
	s_or_b64 exec, exec, s[8:9]
	v_cvt_f32_u32_e32 v5, v3
	s_waitcnt vmcnt(0)
	v_readfirstlane_b32 s2, v4
	v_sub_u32_e32 v4, 0, v3
	v_rcp_iflag_f32_e32 v5, v5
	v_add_u32_e32 v6, s2, v2
	v_mul_f32_e32 v5, 0x4f7ffffe, v5
	v_cvt_u32_f32_e32 v5, v5
	v_mul_lo_u32 v2, v4, v5
	v_mul_hi_u32 v2, v5, v2
	v_add_u32_e32 v2, v5, v2
	v_mul_hi_u32 v2, v6, v2
	v_mul_lo_u32 v4, v2, v3
	v_sub_u32_e32 v4, v6, v4
	v_add_u32_e32 v5, 1, v2
	v_cmp_ge_u32_e32 vcc, v4, v3
	s_nop 1
	v_cndmask_b32_e32 v2, v2, v5, vcc
	v_sub_u32_e32 v5, v4, v3
	v_cndmask_b32_e32 v4, v4, v5, vcc
	v_add_u32_e32 v5, 1, v2
	v_cmp_ge_u32_e32 vcc, v4, v3
	v_add_u32_e32 v4, 1, v6
	s_nop 0
	v_cndmask_b32_e32 v2, v2, v5, vcc
	v_mul_lo_u32 v5, v3, v2
	v_add_u32_e32 v253, 1, v2
	v_add_u32_e32 v3, v5, v3
	v_cmp_ne_u32_e32 vcc, v4, v3
	s_and_saveexec_b64 s[2:3], vcc
	s_xor_b64 s[6:7], exec, s[2:3]
	s_cbranch_execz .LBB0_1386
	s_waitcnt lgkmcnt(0)
	v_mov_b32_e32 v1, 0x2000
	global_load_dword v1, v1, s[4:5] offset:1024 sc1
	s_add_u32 s12, s4, 0x2400
	s_addc_u32 s13, s5, 0
	s_waitcnt vmcnt(0)
	v_cmp_eq_u32_e32 vcc, v1, v2
	s_and_saveexec_b64 s[8:9], vcc
	s_cbranch_execz .LBB0_1385
	s_add_u32 s10, s90, 0x4200
	s_addc_u32 s11, s91, 0
	s_mov_b32 s2, 1
	s_mov_b64 s[14:15], 0
	v_mov_b32_e32 v1, 0
	s_branch .LBB0_1376

; __device__ __forceinline__ unsigned xb_ld(unsigned* p)              { return __hip_atomic_load(p, __ATOMIC_RELAXED, __HIP_MEMORY_SCOPE_AGENT); }
; __device__ __forceinline__ unsigned xb_add(unsigned* p, unsigned v) { return __hip_atomic_fetch_add(p, v, __ATOMIC_RELAXED, __HIP_MEMORY_SCOPE_AGENT); }
; #define XB_SPIN(cond, bar) do { unsigned _sp = 0; while (cond) { __builtin_amdgcn_s_sleep(1); \
;     if ((++_sp & 255u) == 0u) { if (xb_ld(&(bar)[XB_TMO])) break; if (_sp > XB_SPIN_CAP) { atomicAdd(&(bar)[XB_TMO], 1u); break; } } } } while (0)
; __device__ __forceinline__ void xcd_barrier(const XcdBarrier& b) {
;     ...
;             if (og + 1u == (tg + 1u) * nx) xb_add(&bar[XB_TOPGEN], 1u);
;             else XB_SPIN(xb_ld(&bar[XB_TOPGEN]) == tg, bar);
;             __builtin_amdgcn_fence(__ATOMIC_ACQUIRE, "agent");
;             xb_add(&bar[XB_XGEN(b.x)], 1u);
;             asm volatile("s_waitcnt vmcnt(0)" ::: "memory");
.LBB0_1403:
	s_or_b64 exec, exec, s[6:7]
	s_mov_b64 s[6:7], exec
	v_mbcnt_lo_u32_b32 v1, s6, 0
	v_mbcnt_hi_u32_b32 v1, s7, v1
	v_cmp_eq_u32_e32 vcc, 0, v1
	s_waitcnt vmcnt(0)
	buffer_inv sc1
	s_and_saveexec_b64 s[8:9], vcc
	s_cbranch_execz .LBB0_1405
	s_bcnt1_i32_b64 s2, s[6:7]
	v_mov_b32_e32 v1, 0x2000
	v_mov_b32_e32 v2, s2
	global_store_dword v1, v253, s[4:5] offset:1024

; __device__ __forceinline__ unsigned xb_ld(unsigned* p)              { return __hip_atomic_load(p, __ATOMIC_RELAXED, __HIP_MEMORY_SCOPE_AGENT); }
; __device__ __forceinline__ unsigned xb_add(unsigned* p, unsigned v) { return __hip_atomic_fetch_add(p, v, __ATOMIC_RELAXED, __HIP_MEMORY_SCOPE_AGENT); }
; #define XB_SPIN(cond, bar) do { unsigned _sp = 0; while (cond) { __builtin_amdgcn_s_sleep(1); \
;     if ((++_sp & 255u) == 0u) { if (xb_ld(&(bar)[XB_TMO])) break; if (_sp > XB_SPIN_CAP) { atomicAdd(&(bar)[XB_TMO], 1u); break; } } } } while (0)
; __device__ __forceinline__ void xcd_barrier(const XcdBarrier& b) {
;     ...
;         const unsigned old = xb_add(&bar[XB_XSUB(b.x)], 1u);
;         const unsigned gen = old / nloc;
;         if (old + 1u == (gen + 1u) * nloc) {
;             __builtin_amdgcn_fence(__ATOMIC_RELEASE, "agent");
;             asm volatile("s_waitcnt vmcnt(0)" ::: "memory");
;             const unsigned og = xb_add(&bar[XB_TOP], 1u);
;             const unsigned tg = og / nx;
;             if (og + 1u == (tg + 1u) * nx) xb_add(&bar[XB_TOPGEN], 1u);
;             else XB_SPIN(xb_ld(&bar[XB_TOPGEN]) == tg, bar);
;             __builtin_amdgcn_fence(__ATOMIC_ACQUIRE, "agent");
;             xb_add(&bar[XB_XGEN(b.x)], 1u);
;             asm volatile("s_waitcnt vmcnt(0)" ::: "memory");
;         } else {
;             XB_SPIN(xb_ld(&bar[XB_XGEN(b.x)]) == gen, bar);
.LBB0_1451:
	s_or_b64 exec, exec, s[6:7]
	v_cvt_f32_u32_e32 v5, v3
	s_waitcnt vmcnt(0)
	v_readfirstlane_b32 s4, v4
	v_sub_u32_e32 v4, 0, v3
	v_rcp_iflag_f32_e32 v5, v5
	v_add_u32_e32 v6, s4, v2
	v_mul_f32_e32 v5, 0x4f7ffffe, v5
	v_cvt_u32_f32_e32 v5, v5
	v_mul_lo_u32 v2, v4, v5
	v_mul_hi_u32 v2, v5, v2
	v_add_u32_e32 v2, v5, v2
	v_mul_hi_u32 v2, v6, v2
	v_mul_lo_u32 v4, v2, v3
	v_sub_u32_e32 v4, v6, v4
	v_add_u32_e32 v5, 1, v2
	v_cmp_ge_u32_e32 vcc, v4, v3
	s_nop 1
	v_cndmask_b32_e32 v2, v2, v5, vcc
	v_sub_u32_e32 v5, v4, v3
	v_cndmask_b32_e32 v4, v4, v5, vcc
	v_add_u32_e32 v5, 1, v2
	v_cmp_ge_u32_e32 vcc, v4, v3
	v_add_u32_e32 v4, 1, v6
	s_nop 0
	v_cndmask_b32_e32 v2, v2, v5, vcc
	v_mul_lo_u32 v5, v3, v2
	v_add_u32_e32 v253, 1, v2
	v_add_u32_e32 v3, v5, v3
	v_cmp_ne_u32_e32 vcc, v4, v3
	s_and_saveexec_b64 s[4:5], vcc
	s_xor_b64 s[4:5], exec, s[4:5]
	s_cbranch_execz .LBB0_1465
	s_waitcnt lgkmcnt(0)
	v_mov_b32_e32 v1, 0x2000
	global_load_dword v1, v1, s[2:3] offset:1024 sc1
	s_add_u32 s10, s2, 0x2400
	s_addc_u32 s11, s3, 0
	s_waitcnt vmcnt(0)
	v_cmp_eq_u32_e32 vcc, v1, v2
	s_and_saveexec_b64 s[6:7], vcc
	s_cbranch_execz .LBB0_1464
	s_add_u32 s8, s90, 0x4200
	s_addc_u32 s9, s91, 0
	s_mov_b32 s22, 1
	s_mov_b64 s[12:13], 0
	v_mov_b32_e32 v1, 0
	s_branch .LBB0_1455

; __device__ __forceinline__ unsigned xb_ld(unsigned* p)              { return __hip_atomic_load(p, __ATOMIC_RELAXED, __HIP_MEMORY_SCOPE_AGENT); }
; __device__ __forceinline__ unsigned xb_add(unsigned* p, unsigned v) { return __hip_atomic_fetch_add(p, v, __ATOMIC_RELAXED, __HIP_MEMORY_SCOPE_AGENT); }
; #define XB_SPIN(cond, bar) do { unsigned _sp = 0; while (cond) { __builtin_amdgcn_s_sleep(1); \
;     if ((++_sp & 255u) == 0u) { if (xb_ld(&(bar)[XB_TMO])) break; if (_sp > XB_SPIN_CAP) { atomicAdd(&(bar)[XB_TMO], 1u); break; } } } } while (0)
; __device__ __forceinline__ void xcd_barrier(const XcdBarrier& b) {
;     ...
;             if (og + 1u == (tg + 1u) * nx) xb_add(&bar[XB_TOPGEN], 1u);
;             else XB_SPIN(xb_ld(&bar[XB_TOPGEN]) == tg, bar);
;             __builtin_amdgcn_fence(__ATOMIC_ACQUIRE, "agent");
;             xb_add(&bar[XB_XGEN(b.x)], 1u);
;             asm volatile("s_waitcnt vmcnt(0)" ::: "memory");
.LBB0_1482:
	s_or_b64 exec, exec, s[4:5]
	s_mov_b64 s[4:5], exec
	v_mbcnt_lo_u32_b32 v1, s4, 0
	v_mbcnt_hi_u32_b32 v1, s5, v1
	v_cmp_eq_u32_e32 vcc, 0, v1
	s_waitcnt vmcnt(0)
	buffer_inv sc1
	s_and_saveexec_b64 s[6:7], vcc
	s_cbranch_execz .LBB0_1484
	s_bcnt1_i32_b64 s4, s[4:5]
	v_mov_b32_e32 v1, 0x2000
	v_mov_b32_e32 v2, s4
	global_store_dword v1, v253, s[2:3] offset:1024

; __device__ __forceinline__ unsigned xb_ld(unsigned* p)              { return __hip_atomic_load(p, __ATOMIC_RELAXED, __HIP_MEMORY_SCOPE_AGENT); }
; __device__ __forceinline__ unsigned xb_add(unsigned* p, unsigned v) { return __hip_atomic_fetch_add(p, v, __ATOMIC_RELAXED, __HIP_MEMORY_SCOPE_AGENT); }
; #define XB_SPIN(cond, bar) do { unsigned _sp = 0; while (cond) { __builtin_amdgcn_s_sleep(1); \
;     if ((++_sp & 255u) == 0u) { if (xb_ld(&(bar)[XB_TMO])) break; if (_sp > XB_SPIN_CAP) { atomicAdd(&(bar)[XB_TMO], 1u); break; } } } } while (0)
; __device__ __forceinline__ void xcd_barrier(const XcdBarrier& b) {
;     ...
;         const unsigned old = xb_add(&bar[XB_XSUB(b.x)], 1u);
;         const unsigned gen = old / nloc;
;         if (old + 1u == (gen + 1u) * nloc) {
;             __builtin_amdgcn_fence(__ATOMIC_RELEASE, "agent");
;             asm volatile("s_waitcnt vmcnt(0)" ::: "memory");
;             const unsigned og = xb_add(&bar[XB_TOP], 1u);
;             const unsigned tg = og / nx;
;             if (og + 1u == (tg + 1u) * nx) xb_add(&bar[XB_TOPGEN], 1u);
;             else XB_SPIN(xb_ld(&bar[XB_TOPGEN]) == tg, bar);
;             __builtin_amdgcn_fence(__ATOMIC_ACQUIRE, "agent");
;             xb_add(&bar[XB_XGEN(b.x)], 1u);
;             asm volatile("s_waitcnt vmcnt(0)" ::: "memory");
;         } else {
;             XB_SPIN(xb_ld(&bar[XB_XGEN(b.x)]) == gen, bar);
.LBB0_1512:
	s_or_b64 exec, exec, s[8:9]
	v_cvt_f32_u32_e32 v5, v3
	s_waitcnt vmcnt(0)
	v_readfirstlane_b32 s6, v4
	v_sub_u32_e32 v4, 0, v3
	v_rcp_iflag_f32_e32 v5, v5
	v_add_u32_e32 v6, s6, v2
	v_mul_f32_e32 v5, 0x4f7ffffe, v5
	v_cvt_u32_f32_e32 v5, v5
	v_mul_lo_u32 v2, v4, v5
	v_mul_hi_u32 v2, v5, v2
	v_add_u32_e32 v2, v5, v2
	v_mul_hi_u32 v2, v6, v2
	v_mul_lo_u32 v4, v2, v3
	v_sub_u32_e32 v4, v6, v4
	v_add_u32_e32 v5, 1, v2
	v_cmp_ge_u32_e32 vcc, v4, v3
	s_nop 1
	v_cndmask_b32_e32 v2, v2, v5, vcc
	v_sub_u32_e32 v5, v4, v3
	v_cndmask_b32_e32 v4, v4, v5, vcc
	v_add_u32_e32 v5, 1, v2
	v_cmp_ge_u32_e32 vcc, v4, v3
	v_add_u32_e32 v4, 1, v6
	s_nop 0
	v_cndmask_b32_e32 v2, v2, v5, vcc
	v_mul_lo_u32 v5, v3, v2
	v_add_u32_e32 v253, 1, v2
	v_add_u32_e32 v3, v5, v3
	v_cmp_ne_u32_e32 vcc, v4, v3
	s_and_saveexec_b64 s[6:7], vcc
	s_xor_b64 s[6:7], exec, s[6:7]
	s_cbranch_execz .LBB0_1526
	s_waitcnt lgkmcnt(0)
	v_mov_b32_e32 v1, 0x2000
	global_load_dword v1, v1, s[2:3] offset:1024 sc1
	s_add_u32 s12, s2, 0x2400
	s_addc_u32 s13, s3, 0
	s_waitcnt vmcnt(0)
	v_cmp_eq_u32_e32 vcc, v1, v2
	s_and_saveexec_b64 s[8:9], vcc
	s_cbranch_execz .LBB0_1525
	s_add_u32 s10, s90, 0x4200
	s_addc_u32 s11, s91, 0
	s_mov_b32 s24, 1
	s_mov_b64 s[14:15], 0
	v_mov_b32_e32 v1, 0
	s_branch .LBB0_1516

; __device__ __forceinline__ unsigned xb_ld(unsigned* p)              { return __hip_atomic_load(p, __ATOMIC_RELAXED, __HIP_MEMORY_SCOPE_AGENT); }
; __device__ __forceinline__ unsigned xb_add(unsigned* p, unsigned v) { return __hip_atomic_fetch_add(p, v, __ATOMIC_RELAXED, __HIP_MEMORY_SCOPE_AGENT); }
; #define XB_SPIN(cond, bar) do { unsigned _sp = 0; while (cond) { __builtin_amdgcn_s_sleep(1); \
;     if ((++_sp & 255u) == 0u) { if (xb_ld(&(bar)[XB_TMO])) break; if (_sp > XB_SPIN_CAP) { atomicAdd(&(bar)[XB_TMO], 1u); break; } } } } while (0)
; __device__ __forceinline__ void xcd_barrier(const XcdBarrier& b) {
;     ...
;             if (og + 1u == (tg + 1u) * nx) xb_add(&bar[XB_TOPGEN], 1u);
;             else XB_SPIN(xb_ld(&bar[XB_TOPGEN]) == tg, bar);
;             __builtin_amdgcn_fence(__ATOMIC_ACQUIRE, "agent");
;             xb_add(&bar[XB_XGEN(b.x)], 1u);
;             asm volatile("s_waitcnt vmcnt(0)" ::: "memory");
.LBB0_1543:
	s_or_b64 exec, exec, s[6:7]
	s_mov_b64 s[6:7], exec
	v_mbcnt_lo_u32_b32 v1, s6, 0
	v_mbcnt_hi_u32_b32 v1, s7, v1
	v_cmp_eq_u32_e32 vcc, 0, v1
	s_waitcnt vmcnt(0)
	buffer_inv sc1
	s_and_saveexec_b64 s[8:9], vcc
	s_cbranch_execz .LBB0_1545
	s_bcnt1_i32_b64 s6, s[6:7]
	v_mov_b32_e32 v1, 0x2000
	v_mov_b32_e32 v2, s6
	global_store_dword v1, v253, s[2:3] offset:1024

; __device__ __forceinline__ unsigned xb_ld(unsigned* p)              { return __hip_atomic_load(p, __ATOMIC_RELAXED, __HIP_MEMORY_SCOPE_AGENT); }
; __device__ __forceinline__ unsigned xb_add(unsigned* p, unsigned v) { return __hip_atomic_fetch_add(p, v, __ATOMIC_RELAXED, __HIP_MEMORY_SCOPE_AGENT); }
; #define XB_SPIN(cond, bar) do { unsigned _sp = 0; while (cond) { __builtin_amdgcn_s_sleep(1); \
;     if ((++_sp & 255u) == 0u) { if (xb_ld(&(bar)[XB_TMO])) break; if (_sp > XB_SPIN_CAP) { atomicAdd(&(bar)[XB_TMO], 1u); break; } } } } while (0)
; __device__ __forceinline__ void xcd_barrier(const XcdBarrier& b) {
;     ...
;         const unsigned old = xb_add(&bar[XB_XSUB(b.x)], 1u);
;         const unsigned gen = old / nloc;
;         if (old + 1u == (gen + 1u) * nloc) {
;             __builtin_amdgcn_fence(__ATOMIC_RELEASE, "agent");
;             asm volatile("s_waitcnt vmcnt(0)" ::: "memory");
;             const unsigned og = xb_add(&bar[XB_TOP], 1u);
;             const unsigned tg = og / nx;
;             if (og + 1u == (tg + 1u) * nx) xb_add(&bar[XB_TOPGEN], 1u);
;             else XB_SPIN(xb_ld(&bar[XB_TOPGEN]) == tg, bar);
;             __builtin_amdgcn_fence(__ATOMIC_ACQUIRE, "agent");
;             xb_add(&bar[XB_XGEN(b.x)], 1u);
;             asm volatile("s_waitcnt vmcnt(0)" ::: "memory");
;         } else {
;             XB_SPIN(xb_ld(&bar[XB_XGEN(b.x)]) == gen, bar);
.LBB0_1689:
	s_or_b64 exec, exec, s[8:9]
	v_cvt_f32_u32_e32 v4, v2
	s_waitcnt vmcnt(0)
	v_readfirstlane_b32 s6, v3
	v_sub_u32_e32 v3, 0, v2
	v_rcp_iflag_f32_e32 v4, v4
	v_add_u32_e32 v5, s6, v1
	v_mul_f32_e32 v4, 0x4f7ffffe, v4
	v_cvt_u32_f32_e32 v4, v4
	v_mul_lo_u32 v1, v3, v4
	v_mul_hi_u32 v1, v4, v1
	v_add_u32_e32 v1, v4, v1
	v_mul_hi_u32 v1, v5, v1
	v_mul_lo_u32 v3, v1, v2
	v_sub_u32_e32 v3, v5, v3
	v_add_u32_e32 v4, 1, v1
	v_cmp_ge_u32_e32 vcc, v3, v2
	s_nop 1
	v_cndmask_b32_e32 v1, v1, v4, vcc
	v_sub_u32_e32 v4, v3, v2
	v_cndmask_b32_e32 v3, v3, v4, vcc
	v_add_u32_e32 v4, 1, v1
	v_cmp_ge_u32_e32 vcc, v3, v2
	v_add_u32_e32 v3, 1, v5
	s_nop 0
	v_cndmask_b32_e32 v1, v1, v4, vcc
	v_mul_lo_u32 v4, v2, v1
	v_add_u32_e32 v253, 1, v1
	v_add_u32_e32 v2, v4, v2
	v_cmp_ne_u32_e32 vcc, v3, v2
	s_and_saveexec_b64 s[6:7], vcc
	s_xor_b64 s[6:7], exec, s[6:7]
	s_cbranch_execz .LBB0_1703
	s_waitcnt lgkmcnt(0)
	v_mov_b32_e32 v0, 0x2000
	global_load_dword v0, v0, s[2:3] offset:1024 sc1
	s_add_u32 s12, s2, 0x2400
	s_addc_u32 s13, s3, 0
	s_waitcnt vmcnt(0)
	v_cmp_eq_u32_e32 vcc, v0, v1
	s_and_saveexec_b64 s[8:9], vcc
	s_cbranch_execz .LBB0_1702
	s_add_u32 s10, s90, 0x4200
	s_addc_u32 s11, s91, 0
	s_mov_b32 s24, 1
	s_mov_b64 s[14:15], 0
	v_mov_b32_e32 v0, 0
	s_branch .LBB0_1693

; __device__ __forceinline__ unsigned xb_ld(unsigned* p)              { return __hip_atomic_load(p, __ATOMIC_RELAXED, __HIP_MEMORY_SCOPE_AGENT); }
; __device__ __forceinline__ unsigned xb_add(unsigned* p, unsigned v) { return __hip_atomic_fetch_add(p, v, __ATOMIC_RELAXED, __HIP_MEMORY_SCOPE_AGENT); }
; #define XB_SPIN(cond, bar) do { unsigned _sp = 0; while (cond) { __builtin_amdgcn_s_sleep(1); \
;     if ((++_sp & 255u) == 0u) { if (xb_ld(&(bar)[XB_TMO])) break; if (_sp > XB_SPIN_CAP) { atomicAdd(&(bar)[XB_TMO], 1u); break; } } } } while (0)
; __device__ __forceinline__ void xcd_barrier(const XcdBarrier& b) {
;     ...
;             if (og + 1u == (tg + 1u) * nx) xb_add(&bar[XB_TOPGEN], 1u);
;             else XB_SPIN(xb_ld(&bar[XB_TOPGEN]) == tg, bar);
;             __builtin_amdgcn_fence(__ATOMIC_ACQUIRE, "agent");
;             xb_add(&bar[XB_XGEN(b.x)], 1u);
;             asm volatile("s_waitcnt vmcnt(0)" ::: "memory");
.LBB0_1720:
	s_or_b64 exec, exec, s[6:7]
	s_mov_b64 s[6:7], exec
	v_mbcnt_lo_u32_b32 v0, s6, 0
	v_mbcnt_hi_u32_b32 v0, s7, v0
	v_cmp_eq_u32_e32 vcc, 0, v0
	s_waitcnt vmcnt(0)
	buffer_inv sc1
	s_and_saveexec_b64 s[8:9], vcc
	s_cbranch_execz .LBB0_1722
	s_bcnt1_i32_b64 s6, s[6:7]
	v_mov_b32_e32 v0, 0x2000
	v_mov_b32_e32 v1, s6
	global_store_dword v0, v253, s[2:3] offset:1024
